# best version plus the phase-0 (context-length) filter w3 loop rewritten the same way as the phase-A instance
# baseline (speedup 1.0000x reference)
; __device__ __forceinline__ void filter_item(const Params& p, int l, int Lf, int t0, float* dst, float* hidT  , int wid0) {
;     ...
; #pragma unroll 16
;     for (int j = 0; j < 64; ++j) {
;         const float wa = w3[j * 1024 + tid], wb = w3[j * 1024 + 512 + tid];
; #pragma unroll
;         for (int g = 0; g < 8; ++g) { const f32x4 hv = *(const f32x4*)(hidT + j * 32 + 4 * g);
; #pragma unroll
;             for (int i = 0; i < 4; ++i) { acc0[4 * g + i] += hv[i] * wa; acc1[4 * g + i] += hv[i] * wb; } }
;     }
.LBB0_877:
	s_waitcnt vmcnt(0)
	v_add_u32_e32 v182, 0xffffc200, v4
	v_ashrrev_i32_e32 v183, 31, v182
	v_lshl_add_u64 v[182:183], v[182:183], 2, s[0:1]
	s_mov_b64 vcc, 0x1000
	global_load_dword v174, v[182:183], off
	global_load_dword v176, v[182:183], off offset:2048
	v_lshl_add_u64 v[182:183], v[182:183], 0, vcc
	global_load_dword v178, v[182:183], off
	global_load_dword v180, v[182:183], off offset:2048
	v_lshl_add_u64 v[182:183], v[182:183], 0, vcc
	s_add_i32 s39, s38, 0x1b800
	v_mov_b32_e32 v186, s39
	ds_read_b128 v[110:113], v186
	ds_read_b128 v[114:117], v186 offset:16
	ds_read_b128 v[118:121], v186 offset:32
	ds_read_b128 v[122:125], v186 offset:48
	ds_read_b128 v[126:129], v186 offset:64
	ds_read_b128 v[130:133], v186 offset:80
	ds_read_b128 v[134:137], v186 offset:96
	ds_read_b128 v[138:141], v186 offset:112
	s_movk_i32 s39, 31
.Lw3_877_loop:
	s_waitcnt lgkmcnt(7)
	s_nop 0
	ds_read_b128 v[142:145], v186 offset:128
	ds_read_b128 v[146:149], v186 offset:144
	ds_read_b128 v[150:153], v186 offset:160
	ds_read_b128 v[154:157], v186 offset:176
	ds_read_b128 v[158:161], v186 offset:192
	ds_read_b128 v[162:165], v186 offset:208
	ds_read_b128 v[166:169], v186 offset:224
	ds_read_b128 v[170:173], v186 offset:240
	s_waitcnt vmcnt(2) lgkmcnt(8)
	v_pk_fma_f32 v[68:69], v[174:175], v[110:111], v[68:69] op_sel_hi:[0,1,1]
	v_pk_fma_f32 v[62:63], v[176:177], v[110:111], v[62:63] op_sel_hi:[0,1,1]
	v_pk_fma_f32 v[66:67], v[174:175], v[112:113], v[66:67] op_sel_hi:[0,1,1]
	v_pk_fma_f32 v[64:65], v[176:177], v[112:113], v[64:65] op_sel_hi:[0,1,1]
	v_pk_fma_f32 v[58:59], v[174:175], v[114:115], v[58:59] op_sel_hi:[0,1,1]
	v_pk_fma_f32 v[56:57], v[176:177], v[114:115], v[56:57] op_sel_hi:[0,1,1]
	v_pk_fma_f32 v[60:61], v[174:175], v[116:117], v[60:61] op_sel_hi:[0,1,1]
	v_pk_fma_f32 v[54:55], v[176:177], v[116:117], v[54:55] op_sel_hi:[0,1,1]
	v_pk_fma_f32 v[52:53], v[174:175], v[118:119], v[52:53] op_sel_hi:[0,1,1]
	v_pk_fma_f32 v[46:47], v[176:177], v[118:119], v[46:47] op_sel_hi:[0,1,1]
	v_pk_fma_f32 v[50:51], v[174:175], v[120:121], v[50:51] op_sel_hi:[0,1,1]
	v_pk_fma_f32 v[48:49], v[176:177], v[120:121], v[48:49] op_sel_hi:[0,1,1]
	v_pk_fma_f32 v[42:43], v[174:175], v[122:123], v[42:43] op_sel_hi:[0,1,1]
	v_pk_fma_f32 v[40:41], v[176:177], v[122:123], v[40:41] op_sel_hi:[0,1,1]
	v_pk_fma_f32 v[44:45], v[174:175], v[124:125], v[44:45] op_sel_hi:[0,1,1]
	v_pk_fma_f32 v[38:39], v[176:177], v[124:125], v[38:39] op_sel_hi:[0,1,1]
	v_pk_fma_f32 v[36:37], v[174:175], v[126:127], v[36:37] op_sel_hi:[0,1,1]
	v_pk_fma_f32 v[30:31], v[176:177], v[126:127], v[30:31] op_sel_hi:[0,1,1]
	v_pk_fma_f32 v[34:35], v[174:175], v[128:129], v[34:35] op_sel_hi:[0,1,1]
	v_pk_fma_f32 v[32:33], v[176:177], v[128:129], v[32:33] op_sel_hi:[0,1,1]
	v_pk_fma_f32 v[26:27], v[174:175], v[130:131], v[26:27] op_sel_hi:[0,1,1]
	v_pk_fma_f32 v[24:25], v[176:177], v[130:131], v[24:25] op_sel_hi:[0,1,1]
	v_pk_fma_f32 v[28:29], v[174:175], v[132:133], v[28:29] op_sel_hi:[0,1,1]
	v_pk_fma_f32 v[22:23], v[176:177], v[132:133], v[22:23] op_sel_hi:[0,1,1]
	v_pk_fma_f32 v[20:21], v[174:175], v[134:135], v[20:21] op_sel_hi:[0,1,1]
	v_pk_fma_f32 v[14:15], v[176:177], v[134:135], v[14:15] op_sel_hi:[0,1,1]
	v_pk_fma_f32 v[18:19], v[174:175], v[136:137], v[18:19] op_sel_hi:[0,1,1]
	v_pk_fma_f32 v[16:17], v[176:177], v[136:137], v[16:17] op_sel_hi:[0,1,1]
	v_pk_fma_f32 v[10:11], v[174:175], v[138:139], v[10:11] op_sel_hi:[0,1,1]
	v_pk_fma_f32 v[6:7], v[176:177], v[138:139], v[6:7] op_sel_hi:[0,1,1]
	v_pk_fma_f32 v[12:13], v[174:175], v[140:141], v[12:13] op_sel_hi:[0,1,1]
	v_pk_fma_f32 v[8:9], v[176:177], v[140:141], v[8:9] op_sel_hi:[0,1,1]
	global_load_dword v174, v[182:183], off
	global_load_dword v176, v[182:183], off offset:2048
	v_lshl_add_u64 v[182:183], v[182:183], 0, vcc
	s_waitcnt lgkmcnt(7)
	s_nop 0
	ds_read_b128 v[110:113], v186 offset:256
	ds_read_b128 v[114:117], v186 offset:272
	ds_read_b128 v[118:121], v186 offset:288
	ds_read_b128 v[122:125], v186 offset:304
	ds_read_b128 v[126:129], v186 offset:320
	ds_read_b128 v[130:133], v186 offset:336
	ds_read_b128 v[134:137], v186 offset:352
	ds_read_b128 v[138:141], v186 offset:368
	s_waitcnt vmcnt(2) lgkmcnt(8)
	v_pk_fma_f32 v[68:69], v[178:179], v[142:143], v[68:69] op_sel_hi:[0,1,1]
	v_pk_fma_f32 v[62:63], v[180:181], v[142:143], v[62:63] op_sel_hi:[0,1,1]
	v_pk_fma_f32 v[66:67], v[178:179], v[144:145], v[66:67] op_sel_hi:[0,1,1]
	v_pk_fma_f32 v[64:65], v[180:181], v[144:145], v[64:65] op_sel_hi:[0,1,1]
	v_pk_fma_f32 v[58:59], v[178:179], v[146:147], v[58:59] op_sel_hi:[0,1,1]
	v_pk_fma_f32 v[56:57], v[180:181], v[146:147], v[56:57] op_sel_hi:[0,1,1]
	v_pk_fma_f32 v[60:61], v[178:179], v[148:149], v[60:61] op_sel_hi:[0,1,1]
	v_pk_fma_f32 v[54:55], v[180:181], v[148:149], v[54:55] op_sel_hi:[0,1,1]
	v_pk_fma_f32 v[52:53], v[178:179], v[150:151], v[52:53] op_sel_hi:[0,1,1]
	v_pk_fma_f32 v[46:47], v[180:181], v[150:151], v[46:47] op_sel_hi:[0,1,1]
	v_pk_fma_f32 v[50:51], v[178:179], v[152:153], v[50:51] op_sel_hi:[0,1,1]
	v_pk_fma_f32 v[48:49], v[180:181], v[152:153], v[48:49] op_sel_hi:[0,1,1]
	v_pk_fma_f32 v[42:43], v[178:179], v[154:155], v[42:43] op_sel_hi:[0,1,1]
	v_pk_fma_f32 v[40:41], v[180:181], v[154:155], v[40:41] op_sel_hi:[0,1,1]
	v_pk_fma_f32 v[44:45], v[178:179], v[156:157], v[44:45] op_sel_hi:[0,1,1]
	v_pk_fma_f32 v[38:39], v[180:181], v[156:157], v[38:39] op_sel_hi:[0,1,1]
	v_pk_fma_f32 v[36:37], v[178:179], v[158:159], v[36:37] op_sel_hi:[0,1,1]
	v_pk_fma_f32 v[30:31], v[180:181], v[158:159], v[30:31] op_sel_hi:[0,1,1]
	v_pk_fma_f32 v[34:35], v[178:179], v[160:161], v[34:35] op_sel_hi:[0,1,1]
	v_pk_fma_f32 v[32:33], v[180:181], v[160:161], v[32:33] op_sel_hi:[0,1,1]
	v_pk_fma_f32 v[26:27], v[178:179], v[162:163], v[26:27] op_sel_hi:[0,1,1]
	v_pk_fma_f32 v[24:25], v[180:181], v[162:163], v[24:25] op_sel_hi:[0,1,1]
	v_pk_fma_f32 v[28:29], v[178:179], v[164:165], v[28:29] op_sel_hi:[0,1,1]
	v_pk_fma_f32 v[22:23], v[180:181], v[164:165], v[22:23] op_sel_hi:[0,1,1]
	v_pk_fma_f32 v[20:21], v[178:179], v[166:167], v[20:21] op_sel_hi:[0,1,1]
	v_pk_fma_f32 v[14:15], v[180:181], v[166:167], v[14:15] op_sel_hi:[0,1,1]
	v_pk_fma_f32 v[18:19], v[178:179], v[168:169], v[18:19] op_sel_hi:[0,1,1]
	v_pk_fma_f32 v[16:17], v[180:181], v[168:169], v[16:17] op_sel_hi:[0,1,1]
	v_pk_fma_f32 v[10:11], v[178:179], v[170:171], v[10:11] op_sel_hi:[0,1,1]
	v_pk_fma_f32 v[6:7], v[180:181], v[170:171], v[6:7] op_sel_hi:[0,1,1]
	v_pk_fma_f32 v[12:13], v[178:179], v[172:173], v[12:13] op_sel_hi:[0,1,1]
	v_pk_fma_f32 v[8:9], v[180:181], v[172:173], v[8:9] op_sel_hi:[0,1,1]
	global_load_dword v178, v[182:183], off
	global_load_dword v180, v[182:183], off offset:2048
	v_lshl_add_u64 v[182:183], v[182:183], 0, vcc
	v_add_u32_e32 v186, 0x100, v186
	s_add_i32 s39, s39, -1
	s_cmp_lg_u32 s39, 0
	s_cbranch_scc1 .Lw3_877_loop
; __device__ __forceinline__ void filter_item(const Params& p, int l, int Lf, int t0, float* dst, float* hidT  , int wid0) {
;     ...
;     for (int j = 0; j < 64; ++j) {
;         const float wa = w3[j * 1024 + tid], wb = w3[j * 1024 + 512 + tid];
; #pragma unroll
;         for (int g = 0; g < 8; ++g) { const f32x4 hv = *(const f32x4*)(hidT + j * 32 + 4 * g);
; #pragma unroll
;             for (int i = 0; i < 4; ++i) { acc0[4 * g + i] += hv[i] * wa; acc1[4 * g + i] += hv[i] * wb; } }
;     }
;     const float dmin = -3.0701134573253945f, dmax = -15.350567286626973f;
;     const float delta = fabsf(dmin + (float)tid * ((dmax - dmin) / 511.f));
; #pragma unroll
;     for (int g = 0; g < 8; ++g) { f32x4 o0, o1;
; #pragma unroll
;         for (int i = 0; i < 4; ++i) { const float tn = (float)(t0 + 4 * g + i) / (float)(Lf - 1); const float wdw = __expf(-tn * delta); o0[i] = acc0[4 * g + i] * wdw; o1[i] = acc1[4 * g + i] * wdw; }
	s_waitcnt lgkmcnt(7)
	s_nop 0
	ds_read_b128 v[142:145], v186 offset:128
	ds_read_b128 v[146:149], v186 offset:144
	ds_read_b128 v[150:153], v186 offset:160
	ds_read_b128 v[154:157], v186 offset:176
	ds_read_b128 v[158:161], v186 offset:192
	ds_read_b128 v[162:165], v186 offset:208
	ds_read_b128 v[166:169], v186 offset:224
	ds_read_b128 v[170:173], v186 offset:240
	s_waitcnt vmcnt(2) lgkmcnt(8)
	v_pk_fma_f32 v[68:69], v[174:175], v[110:111], v[68:69] op_sel_hi:[0,1,1]
	v_pk_fma_f32 v[62:63], v[176:177], v[110:111], v[62:63] op_sel_hi:[0,1,1]
	v_pk_fma_f32 v[66:67], v[174:175], v[112:113], v[66:67] op_sel_hi:[0,1,1]
	v_pk_fma_f32 v[64:65], v[176:177], v[112:113], v[64:65] op_sel_hi:[0,1,1]
	v_pk_fma_f32 v[58:59], v[174:175], v[114:115], v[58:59] op_sel_hi:[0,1,1]
	v_pk_fma_f32 v[56:57], v[176:177], v[114:115], v[56:57] op_sel_hi:[0,1,1]
	v_pk_fma_f32 v[60:61], v[174:175], v[116:117], v[60:61] op_sel_hi:[0,1,1]
	v_pk_fma_f32 v[54:55], v[176:177], v[116:117], v[54:55] op_sel_hi:[0,1,1]
	v_pk_fma_f32 v[52:53], v[174:175], v[118:119], v[52:53] op_sel_hi:[0,1,1]
	v_pk_fma_f32 v[46:47], v[176:177], v[118:119], v[46:47] op_sel_hi:[0,1,1]
	v_pk_fma_f32 v[50:51], v[174:175], v[120:121], v[50:51] op_sel_hi:[0,1,1]
	v_pk_fma_f32 v[48:49], v[176:177], v[120:121], v[48:49] op_sel_hi:[0,1,1]
	v_pk_fma_f32 v[42:43], v[174:175], v[122:123], v[42:43] op_sel_hi:[0,1,1]
	v_pk_fma_f32 v[40:41], v[176:177], v[122:123], v[40:41] op_sel_hi:[0,1,1]
	v_pk_fma_f32 v[44:45], v[174:175], v[124:125], v[44:45] op_sel_hi:[0,1,1]
	v_pk_fma_f32 v[38:39], v[176:177], v[124:125], v[38:39] op_sel_hi:[0,1,1]
	v_pk_fma_f32 v[36:37], v[174:175], v[126:127], v[36:37] op_sel_hi:[0,1,1]
	v_pk_fma_f32 v[30:31], v[176:177], v[126:127], v[30:31] op_sel_hi:[0,1,1]
	v_pk_fma_f32 v[34:35], v[174:175], v[128:129], v[34:35] op_sel_hi:[0,1,1]
	v_pk_fma_f32 v[32:33], v[176:177], v[128:129], v[32:33] op_sel_hi:[0,1,1]
	v_pk_fma_f32 v[26:27], v[174:175], v[130:131], v[26:27] op_sel_hi:[0,1,1]
	v_pk_fma_f32 v[24:25], v[176:177], v[130:131], v[24:25] op_sel_hi:[0,1,1]
	v_pk_fma_f32 v[28:29], v[174:175], v[132:133], v[28:29] op_sel_hi:[0,1,1]
	v_pk_fma_f32 v[22:23], v[176:177], v[132:133], v[22:23] op_sel_hi:[0,1,1]
	v_pk_fma_f32 v[20:21], v[174:175], v[134:135], v[20:21] op_sel_hi:[0,1,1]
	v_pk_fma_f32 v[14:15], v[176:177], v[134:135], v[14:15] op_sel_hi:[0,1,1]
	v_pk_fma_f32 v[18:19], v[174:175], v[136:137], v[18:19] op_sel_hi:[0,1,1]
	v_pk_fma_f32 v[16:17], v[176:177], v[136:137], v[16:17] op_sel_hi:[0,1,1]
	v_pk_fma_f32 v[10:11], v[174:175], v[138:139], v[10:11] op_sel_hi:[0,1,1]
	v_pk_fma_f32 v[6:7], v[176:177], v[138:139], v[6:7] op_sel_hi:[0,1,1]
	v_pk_fma_f32 v[12:13], v[174:175], v[140:141], v[12:13] op_sel_hi:[0,1,1]
	v_pk_fma_f32 v[8:9], v[176:177], v[140:141], v[8:9] op_sel_hi:[0,1,1]
	s_waitcnt vmcnt(0) lgkmcnt(0)
	v_pk_fma_f32 v[68:69], v[178:179], v[142:143], v[68:69] op_sel_hi:[0,1,1]
	v_pk_fma_f32 v[62:63], v[180:181], v[142:143], v[62:63] op_sel_hi:[0,1,1]
	v_pk_fma_f32 v[66:67], v[178:179], v[144:145], v[66:67] op_sel_hi:[0,1,1]
	v_pk_fma_f32 v[64:65], v[180:181], v[144:145], v[64:65] op_sel_hi:[0,1,1]
	v_pk_fma_f32 v[58:59], v[178:179], v[146:147], v[58:59] op_sel_hi:[0,1,1]
	v_pk_fma_f32 v[56:57], v[180:181], v[146:147], v[56:57] op_sel_hi:[0,1,1]
	v_pk_fma_f32 v[60:61], v[178:179], v[148:149], v[60:61] op_sel_hi:[0,1,1]
	v_pk_fma_f32 v[54:55], v[180:181], v[148:149], v[54:55] op_sel_hi:[0,1,1]
	v_pk_fma_f32 v[52:53], v[178:179], v[150:151], v[52:53] op_sel_hi:[0,1,1]
	v_pk_fma_f32 v[46:47], v[180:181], v[150:151], v[46:47] op_sel_hi:[0,1,1]
	v_pk_fma_f32 v[50:51], v[178:179], v[152:153], v[50:51] op_sel_hi:[0,1,1]
	v_pk_fma_f32 v[48:49], v[180:181], v[152:153], v[48:49] op_sel_hi:[0,1,1]
	v_pk_fma_f32 v[42:43], v[178:179], v[154:155], v[42:43] op_sel_hi:[0,1,1]
	v_pk_fma_f32 v[40:41], v[180:181], v[154:155], v[40:41] op_sel_hi:[0,1,1]
	v_pk_fma_f32 v[44:45], v[178:179], v[156:157], v[44:45] op_sel_hi:[0,1,1]
	v_pk_fma_f32 v[38:39], v[180:181], v[156:157], v[38:39] op_sel_hi:[0,1,1]
	v_pk_fma_f32 v[36:37], v[178:179], v[158:159], v[36:37] op_sel_hi:[0,1,1]
	v_pk_fma_f32 v[30:31], v[180:181], v[158:159], v[30:31] op_sel_hi:[0,1,1]
	v_pk_fma_f32 v[34:35], v[178:179], v[160:161], v[34:35] op_sel_hi:[0,1,1]
	v_pk_fma_f32 v[32:33], v[180:181], v[160:161], v[32:33] op_sel_hi:[0,1,1]
	v_pk_fma_f32 v[26:27], v[178:179], v[162:163], v[26:27] op_sel_hi:[0,1,1]
	v_pk_fma_f32 v[24:25], v[180:181], v[162:163], v[24:25] op_sel_hi:[0,1,1]
	v_pk_fma_f32 v[28:29], v[178:179], v[164:165], v[28:29] op_sel_hi:[0,1,1]
	v_pk_fma_f32 v[22:23], v[180:181], v[164:165], v[22:23] op_sel_hi:[0,1,1]
	v_pk_fma_f32 v[20:21], v[178:179], v[166:167], v[20:21] op_sel_hi:[0,1,1]
	v_pk_fma_f32 v[14:15], v[180:181], v[166:167], v[14:15] op_sel_hi:[0,1,1]
	v_pk_fma_f32 v[18:19], v[178:179], v[168:169], v[18:19] op_sel_hi:[0,1,1]
	v_pk_fma_f32 v[16:17], v[180:181], v[168:169], v[16:17] op_sel_hi:[0,1,1]
	v_pk_fma_f32 v[10:11], v[178:179], v[170:171], v[10:11] op_sel_hi:[0,1,1]
	v_pk_fma_f32 v[6:7], v[180:181], v[170:171], v[6:7] op_sel_hi:[0,1,1]
	v_pk_fma_f32 v[12:13], v[178:179], v[172:173], v[12:13] op_sel_hi:[0,1,1]
	v_pk_fma_f32 v[8:9], v[180:181], v[172:173], v[8:9] op_sel_hi:[0,1,1]
	s_mov_b32 s38, 0
	v_add_u32_e32 v4, 0x10000, v4
	s_lshl_b64 s[0:1], s[34:35], 20
	v_readlane_b32 s4, v251, 43
	s_add_u32 s0, s4, s0
	v_readlane_b32 s4, v251, 44
	s_addc_u32 s1, s4, s1
	v_cvt_f32_ubyte0_e32 v5, s27
	s_mov_b32 s4, 0xc37f0000
	v_div_scale_f32 v70, s[38:39], s4, s4, v5
	v_rcp_f32_e32 v71, v70
	v_ashrrev_i32_e32 v3, 31, v2
	v_cvt_f32_i32_e32 v4, v0
	v_lshlrev_b64 v[0:1], 10, v[0:1]
	v_fma_f32 v72, -v70, v71, 1.0
; __device__ __forceinline__ void filter_item(const Params& p, int l, int Lf, int t0, float* dst, float* hidT  , int wid0) {
;     ...
;     const float dmin = -3.0701134573253945f, dmax = -15.350567286626973f;
;     const float delta = fabsf(dmin + (float)tid * ((dmax - dmin) / 511.f));
; #pragma unroll
;     for (int g = 0; g < 8; ++g) { f32x4 o0, o1;
; #pragma unroll
;         for (int i = 0; i < 4; ++i) { const float tn = (float)(t0 + 4 * g + i) / (float)(Lf - 1); const float wdw = __expf(-tn * delta); o0[i] = acc0[4 * g + i] * wdw; o1[i] = acc1[4 * g + i] * wdw; }
;         *(f32x4*)(dst + (size_t)tid * Lf + t0 + 4 * g) = o0; *(f32x4*)(dst + (size_t)(512 + tid) * Lf + t0 + 4 * g) = o1; }
	v_fmac_f32_e32 v71, v72, v71
	v_div_scale_f32 v72, vcc, v5, s4, v5
	v_mul_f32_e32 v73, v72, v71
	v_fma_f32 v74, -v70, v73, v72
	v_fmac_f32_e32 v73, v74, v71
	v_lshlrev_b64 v[2:3], 10, v[2:3]
	v_fma_f32 v70, -v70, v73, v72
	v_lshl_add_u64 v[0:1], s[0:1], 0, v[0:1]
	v_lshl_add_u64 v[2:3], s[0:1], 0, v[2:3]
	v_div_fmas_f32 v70, v70, v71, v73
	s_or_b32 s0, s27, 1
	v_div_fixup_f32 v5, v70, s4, v5
	v_cvt_f32_ubyte0_e32 v70, s0
	v_div_scale_f32 v71, s[0:1], s4, s4, v70
	v_rcp_f32_e32 v73, v71
	v_fmamk_f32 v4, v4, 0xbcc4df2d, v219
	v_mul_f32_e64 v5, v5, |v4|
	v_mul_f32_e32 v5, 0x3fb8aa3b, v5
	v_exp_f32_e32 v72, v5
	v_fma_f32 v5, -v71, v73, 1.0
	v_fmac_f32_e32 v73, v5, v73
	v_div_scale_f32 v5, vcc, v70, s4, v70
	v_mul_f32_e32 v74, v5, v73
	v_fma_f32 v75, -v71, v74, v5
	v_fmac_f32_e32 v74, v75, v73
	v_fma_f32 v5, -v71, v74, v5
	v_div_fmas_f32 v5, v5, v73, v74
	s_or_b32 s0, s27, 2
	v_div_fixup_f32 v5, v5, s4, v70
	v_cvt_f32_ubyte0_e32 v70, s0
	v_div_scale_f32 v71, s[0:1], s4, s4, v70
	v_rcp_f32_e32 v74, v71
	v_mul_f32_e64 v5, v5, |v4|
	v_mul_f32_e32 v5, 0x3fb8aa3b, v5
	v_exp_f32_e32 v73, v5
	v_fma_f32 v5, -v71, v74, 1.0
	v_fmac_f32_e32 v74, v5, v74
	v_div_scale_f32 v5, vcc, v70, s4, v70
	v_mul_f32_e32 v75, v5, v74
	v_fma_f32 v76, -v71, v75, v5
	v_fmac_f32_e32 v75, v76, v74
	v_fma_f32 v5, -v71, v75, v5
	v_div_fmas_f32 v5, v5, v74, v75
	s_or_b32 s0, s27, 3
	v_div_fixup_f32 v5, v5, s4, v70
	v_cvt_f32_ubyte0_e32 v70, s0
	v_div_scale_f32 v71, s[0:1], s4, s4, v70
	v_rcp_f32_e32 v75, v71
	v_mul_f32_e64 v5, v5, |v4|
	v_mul_f32_e32 v5, 0x3fb8aa3b, v5
	v_exp_f32_e32 v74, v5
	v_fma_f32 v5, -v71, v75, 1.0
	v_fmac_f32_e32 v75, v5, v75
	v_div_scale_f32 v5, vcc, v70, s4, v70
	v_mul_f32_e32 v76, v5, v75
	v_fma_f32 v77, -v71, v76, v5
	v_fmac_f32_e32 v76, v77, v75
	v_fma_f32 v5, -v71, v76, v5
	v_div_fmas_f32 v5, v5, v75, v76
	v_div_fixup_f32 v5, v5, s4, v70
	v_mul_f32_e64 v5, v5, |v4|
	v_mul_f32_e32 v5, 0x3fb8aa3b, v5
	s_or_b32 s0, s27, 4
	v_exp_f32_e32 v75, v5
	v_cvt_f32_ubyte0_e32 v5, s0
	v_div_scale_f32 v76, s[0:1], s4, s4, v5
	v_rcp_f32_e32 v77, v76
	v_pk_mul_f32 v[70:71], v[74:75], v[66:67]
	v_pk_mul_f32 v[68:69], v[72:73], v[68:69]
	v_pk_mul_f32 v[62:63], v[72:73], v[62:63]
	v_fma_f32 v66, -v76, v77, 1.0
	v_fmac_f32_e32 v77, v66, v77
	v_div_scale_f32 v66, vcc, v5, s4, v5
	v_mul_f32_e32 v67, v66, v77
	v_fma_f32 v72, -v76, v67, v66
	v_fmac_f32_e32 v67, v72, v77
	v_fma_f32 v66, -v76, v67, v66
	s_or_b32 s0, s27, 5
	v_div_fmas_f32 v66, v66, v77, v67
	v_cvt_f32_ubyte0_e32 v67, s0
	v_div_scale_f32 v72, s[0:1], s4, s4, v67
	v_rcp_f32_e32 v73, v72
	v_div_fixup_f32 v5, v66, s4, v5
	v_mul_f32_e64 v5, v5, |v4|
	v_mul_f32_e32 v5, 0x3fb8aa3b, v5
	v_exp_f32_e32 v66, v5
	v_fma_f32 v5, -v72, v73, 1.0
	v_fmac_f32_e32 v73, v5, v73
	v_div_scale_f32 v5, vcc, v67, s4, v67
	v_pk_mul_f32 v[64:65], v[74:75], v[64:65]
	v_mul_f32_e32 v74, v5, v73
	v_fma_f32 v75, -v72, v74, v5
	v_fmac_f32_e32 v74, v75, v73
	s_or_b32 s0, s27, 6
	v_fma_f32 v5, -v72, v74, v5
	v_cvt_f32_ubyte0_e32 v72, s0
	v_div_fmas_f32 v5, v5, v73, v74
	v_div_scale_f32 v73, s[0:1], s4, s4, v72
	v_rcp_f32_e32 v74, v73
	v_div_fixup_f32 v5, v5, s4, v67
	v_mul_f32_e64 v5, v5, |v4|
	v_mul_f32_e32 v5, 0x3fb8aa3b, v5
	v_exp_f32_e32 v67, v5
	v_fma_f32 v5, -v73, v74, 1.0
	v_fmac_f32_e32 v74, v5, v74
	v_div_scale_f32 v5, vcc, v72, s4, v72
	v_mul_f32_e32 v75, v5, v74
	v_fma_f32 v76, -v73, v75, v5
	v_fmac_f32_e32 v75, v76, v74
	s_or_b32 s0, s27, 7
	v_fma_f32 v5, -v73, v75, v5
	v_cvt_f32_ubyte0_e32 v73, s0
	v_div_fmas_f32 v5, v5, v74, v75
	v_div_scale_f32 v74, s[0:1], s4, s4, v73
	v_rcp_f32_e32 v75, v74
	v_div_fixup_f32 v5, v5, s4, v72
	v_mul_f32_e64 v5, v5, |v4|
	v_mul_f32_e32 v5, 0x3fb8aa3b, v5
	v_exp_f32_e32 v72, v5
	v_fma_f32 v5, -v74, v75, 1.0
	v_fmac_f32_e32 v75, v5, v75
	v_div_scale_f32 v5, vcc, v73, s4, v73
	v_mul_f32_e32 v76, v5, v75
	v_fma_f32 v77, -v74, v76, v5
	v_fmac_f32_e32 v76, v77, v75
	v_fma_f32 v5, -v74, v76, v5
	v_div_fmas_f32 v5, v5, v75, v76
	v_div_fixup_f32 v5, v5, s4, v73
	v_mul_f32_e64 v5, v5, |v4|
	s_lshl_b32 s34, s27, 2
	s_mov_b32 s35, s92
	v_mul_f32_e32 v5, 0x3fb8aa3b, v5
	s_or_b32 s0, s27, 8
	v_lshl_add_u64 v[0:1], v[0:1], 0, s[34:35]
	v_exp_f32_e32 v73, v5
	v_cvt_f32_ubyte0_e32 v5, s0
	v_lshl_add_u64 v[2:3], v[2:3], 0, s[34:35]
	global_store_dwordx4 v[0:1], v[68:71], off
	global_store_dwordx4 v[2:3], v[62:65], off
	v_pk_mul_f32 v[58:59], v[66:67], v[58:59]
	v_pk_mul_f32 v[60:61], v[72:73], v[60:61]
	v_pk_mul_f32 v[62:63], v[66:67], v[56:57]
	v_div_scale_f32 v56, s[0:1], s4, s4, v5
	v_rcp_f32_e32 v57, v56
	v_pk_mul_f32 v[64:65], v[72:73], v[54:55]
	global_store_dwordx4 v[0:1], v[58:61], off offset:16
	global_store_dwordx4 v[2:3], v[62:65], off offset:16
	s_or_b32 s0, s27, 9
	v_fma_f32 v54, -v56, v57, 1.0
	v_fmac_f32_e32 v57, v54, v57
	v_div_scale_f32 v54, vcc, v5, s4, v5
	v_mul_f32_e32 v55, v54, v57
	v_fma_f32 v58, -v56, v55, v54
	v_fmac_f32_e32 v55, v58, v57
	v_fma_f32 v54, -v56, v55, v54
	v_div_fmas_f32 v54, v54, v57, v55
	v_div_fixup_f32 v5, v54, s4, v5
	v_cvt_f32_ubyte0_e32 v54, s0
	v_div_scale_f32 v55, s[0:1], s4, s4, v54
	v_rcp_f32_e32 v57, v55
	v_mul_f32_e64 v5, v5, |v4|
	v_mul_f32_e32 v5, 0x3fb8aa3b, v5
	v_exp_f32_e32 v56, v5
	v_fma_f32 v5, -v55, v57, 1.0
	v_fmac_f32_e32 v57, v5, v57
	v_div_scale_f32 v5, vcc, v54, s4, v54
	v_mul_f32_e32 v58, v5, v57
	v_fma_f32 v59, -v55, v58, v5
	v_fmac_f32_e32 v58, v59, v57
	v_fma_f32 v5, -v55, v58, v5
	v_div_fmas_f32 v5, v5, v57, v58
	s_or_b32 s0, s27, 10
	v_div_fixup_f32 v5, v5, s4, v54
	v_cvt_f32_ubyte0_e32 v54, s0
	v_div_scale_f32 v55, s[0:1], s4, s4, v54
	v_rcp_f32_e32 v58, v55
	v_mul_f32_e64 v5, v5, |v4|
	v_mul_f32_e32 v5, 0x3fb8aa3b, v5
	v_exp_f32_e32 v57, v5
; __device__ __forceinline__ void filter_item(const Params& p, int l, int Lf, int t0, float* dst, float* hidT  , int wid0) {
;     ...
;     const float dmin = -3.0701134573253945f, dmax = -15.350567286626973f;
;     const float delta = fabsf(dmin + (float)tid * ((dmax - dmin) / 511.f));
; #pragma unroll
;     for (int g = 0; g < 8; ++g) { f32x4 o0, o1;
; #pragma unroll
;         for (int i = 0; i < 4; ++i) { const float tn = (float)(t0 + 4 * g + i) / (float)(Lf - 1); const float wdw = __expf(-tn * delta); o0[i] = acc0[4 * g + i] * wdw; o1[i] = acc1[4 * g + i] * wdw; }
;         *(f32x4*)(dst + (size_t)tid * Lf + t0 + 4 * g) = o0; *(f32x4*)(dst + (size_t)(512 + tid) * Lf + t0 + 4 * g) = o1; }
	v_fma_f32 v5, -v55, v58, 1.0
	v_fmac_f32_e32 v58, v5, v58
	v_div_scale_f32 v5, vcc, v54, s4, v54
	v_mul_f32_e32 v59, v5, v58
	v_fma_f32 v60, -v55, v59, v5
	v_fmac_f32_e32 v59, v60, v58
	v_fma_f32 v5, -v55, v59, v5
	v_div_fmas_f32 v5, v5, v58, v59
	s_or_b32 s0, s27, 11
	v_div_fixup_f32 v5, v5, s4, v54
	v_cvt_f32_ubyte0_e32 v54, s0
	v_div_scale_f32 v55, s[0:1], s4, s4, v54
	v_rcp_f32_e32 v59, v55
	v_mul_f32_e64 v5, v5, |v4|
	v_mul_f32_e32 v5, 0x3fb8aa3b, v5
	v_exp_f32_e32 v58, v5
	v_fma_f32 v5, -v55, v59, 1.0
	v_fmac_f32_e32 v59, v5, v59
	v_div_scale_f32 v5, vcc, v54, s4, v54
	v_mul_f32_e32 v60, v5, v59
	v_fma_f32 v61, -v55, v60, v5
	v_fmac_f32_e32 v60, v61, v59
	v_fma_f32 v5, -v55, v60, v5
	v_div_fmas_f32 v5, v5, v59, v60
	v_div_fixup_f32 v5, v5, s4, v54
	v_mul_f32_e64 v5, v5, |v4|
	v_mul_f32_e32 v5, 0x3fb8aa3b, v5
	s_or_b32 s0, s27, 12
	v_exp_f32_e32 v59, v5
	v_cvt_f32_ubyte0_e32 v5, s0
	v_div_scale_f32 v60, s[0:1], s4, s4, v5
	v_rcp_f32_e32 v61, v60
	v_pk_mul_f32 v[54:55], v[58:59], v[50:51]
	v_pk_mul_f32 v[52:53], v[56:57], v[52:53]
	v_pk_mul_f32 v[46:47], v[56:57], v[46:47]
	v_fma_f32 v50, -v60, v61, 1.0
	v_fmac_f32_e32 v61, v50, v61
	v_div_scale_f32 v50, vcc, v5, s4, v5
	v_mul_f32_e32 v51, v50, v61
	v_fma_f32 v56, -v60, v51, v50
	v_fmac_f32_e32 v51, v56, v61
	v_fma_f32 v50, -v60, v51, v50
	s_or_b32 s0, s27, 13
	v_div_fmas_f32 v50, v50, v61, v51
	v_cvt_f32_ubyte0_e32 v51, s0
	v_div_scale_f32 v56, s[0:1], s4, s4, v51
	v_rcp_f32_e32 v57, v56
	v_div_fixup_f32 v5, v50, s4, v5
	v_mul_f32_e64 v5, v5, |v4|
	v_mul_f32_e32 v5, 0x3fb8aa3b, v5
	v_exp_f32_e32 v50, v5
	v_fma_f32 v5, -v56, v57, 1.0
	v_fmac_f32_e32 v57, v5, v57
	v_div_scale_f32 v5, vcc, v51, s4, v51
	v_pk_mul_f32 v[48:49], v[58:59], v[48:49]
	v_mul_f32_e32 v58, v5, v57
	v_fma_f32 v59, -v56, v58, v5
	v_fmac_f32_e32 v58, v59, v57
	s_or_b32 s0, s27, 14
	v_fma_f32 v5, -v56, v58, v5
	v_cvt_f32_ubyte0_e32 v56, s0
	v_div_fmas_f32 v5, v5, v57, v58
	v_div_scale_f32 v57, s[0:1], s4, s4, v56
	v_rcp_f32_e32 v58, v57
	v_div_fixup_f32 v5, v5, s4, v51
	v_mul_f32_e64 v5, v5, |v4|
	v_mul_f32_e32 v5, 0x3fb8aa3b, v5
	v_exp_f32_e32 v51, v5
	v_fma_f32 v5, -v57, v58, 1.0
	v_fmac_f32_e32 v58, v5, v58
	v_div_scale_f32 v5, vcc, v56, s4, v56
	v_mul_f32_e32 v59, v5, v58
	v_fma_f32 v60, -v57, v59, v5
	v_fmac_f32_e32 v59, v60, v58
	s_or_b32 s0, s27, 15
	v_fma_f32 v5, -v57, v59, v5
	v_cvt_f32_ubyte0_e32 v57, s0
	v_div_fmas_f32 v5, v5, v58, v59
	v_div_scale_f32 v58, s[0:1], s4, s4, v57
	v_rcp_f32_e32 v59, v58
	v_div_fixup_f32 v5, v5, s4, v56
	v_mul_f32_e64 v5, v5, |v4|
	v_mul_f32_e32 v5, 0x3fb8aa3b, v5
	v_exp_f32_e32 v56, v5
	v_fma_f32 v5, -v58, v59, 1.0
	v_fmac_f32_e32 v59, v5, v59
	v_div_scale_f32 v5, vcc, v57, s4, v57
	v_mul_f32_e32 v60, v5, v59
	v_fma_f32 v61, -v58, v60, v5
	v_fmac_f32_e32 v60, v61, v59
	v_fma_f32 v5, -v58, v60, v5
	v_div_fmas_f32 v5, v5, v59, v60
	v_div_fixup_f32 v5, v5, s4, v57
	v_mul_f32_e64 v5, v5, |v4|
	v_mul_f32_e32 v5, 0x3fb8aa3b, v5
	s_or_b32 s0, s27, 16
	v_exp_f32_e32 v57, v5
	v_cvt_f32_ubyte0_e32 v5, s0
	global_store_dwordx4 v[0:1], v[52:55], off offset:32
	global_store_dwordx4 v[2:3], v[46:49], off offset:32
	v_pk_mul_f32 v[42:43], v[50:51], v[42:43]
	v_pk_mul_f32 v[44:45], v[56:57], v[44:45]
	v_pk_mul_f32 v[46:47], v[50:51], v[40:41]
	v_div_scale_f32 v40, s[0:1], s4, s4, v5
	v_rcp_f32_e32 v41, v40
	v_pk_mul_f32 v[48:49], v[56:57], v[38:39]
	global_store_dwordx4 v[0:1], v[42:45], off offset:48
	global_store_dwordx4 v[2:3], v[46:49], off offset:48
	s_or_b32 s0, s27, 17
	v_fma_f32 v38, -v40, v41, 1.0
	v_fmac_f32_e32 v41, v38, v41
	v_div_scale_f32 v38, vcc, v5, s4, v5
	v_mul_f32_e32 v39, v38, v41
	v_fma_f32 v42, -v40, v39, v38
	v_fmac_f32_e32 v39, v42, v41
	v_fma_f32 v38, -v40, v39, v38
	v_div_fmas_f32 v38, v38, v41, v39
	v_div_fixup_f32 v5, v38, s4, v5
	v_cvt_f32_ubyte0_e32 v38, s0
	v_div_scale_f32 v39, s[0:1], s4, s4, v38
	v_rcp_f32_e32 v41, v39
	v_mul_f32_e64 v5, v5, |v4|
	v_mul_f32_e32 v5, 0x3fb8aa3b, v5
	v_exp_f32_e32 v40, v5
	v_fma_f32 v5, -v39, v41, 1.0
	v_fmac_f32_e32 v41, v5, v41
	v_div_scale_f32 v5, vcc, v38, s4, v38
	v_mul_f32_e32 v42, v5, v41
	v_fma_f32 v43, -v39, v42, v5
	v_fmac_f32_e32 v42, v43, v41
	v_fma_f32 v5, -v39, v42, v5
	v_div_fmas_f32 v5, v5, v41, v42
	s_or_b32 s0, s27, 18
	v_div_fixup_f32 v5, v5, s4, v38
	v_cvt_f32_ubyte0_e32 v38, s0
	v_div_scale_f32 v39, s[0:1], s4, s4, v38
	v_rcp_f32_e32 v42, v39
	v_mul_f32_e64 v5, v5, |v4|
	v_mul_f32_e32 v5, 0x3fb8aa3b, v5
	v_exp_f32_e32 v41, v5
	v_fma_f32 v5, -v39, v42, 1.0
	v_fmac_f32_e32 v42, v5, v42
	v_div_scale_f32 v5, vcc, v38, s4, v38
	v_mul_f32_e32 v43, v5, v42
	v_fma_f32 v44, -v39, v43, v5
	v_fmac_f32_e32 v43, v44, v42
	v_fma_f32 v5, -v39, v43, v5
	v_div_fmas_f32 v5, v5, v42, v43
	s_or_b32 s0, s27, 19
	v_div_fixup_f32 v5, v5, s4, v38
	v_cvt_f32_ubyte0_e32 v38, s0
	v_div_scale_f32 v39, s[0:1], s4, s4, v38
	v_rcp_f32_e32 v43, v39
	v_mul_f32_e64 v5, v5, |v4|
	v_mul_f32_e32 v5, 0x3fb8aa3b, v5
	v_exp_f32_e32 v42, v5
	v_fma_f32 v5, -v39, v43, 1.0
	v_fmac_f32_e32 v43, v5, v43
	v_div_scale_f32 v5, vcc, v38, s4, v38
	v_mul_f32_e32 v44, v5, v43
	v_fma_f32 v45, -v39, v44, v5
	v_fmac_f32_e32 v44, v45, v43
	v_fma_f32 v5, -v39, v44, v5
	v_div_fmas_f32 v5, v5, v43, v44
	v_div_fixup_f32 v5, v5, s4, v38
	v_mul_f32_e64 v5, v5, |v4|
	v_mul_f32_e32 v5, 0x3fb8aa3b, v5
	s_or_b32 s0, s27, 20
	v_exp_f32_e32 v43, v5
	v_cvt_f32_ubyte0_e32 v5, s0
	v_div_scale_f32 v44, s[0:1], s4, s4, v5
	v_rcp_f32_e32 v45, v44
	v_pk_mul_f32 v[38:39], v[42:43], v[34:35]
	v_pk_mul_f32 v[36:37], v[40:41], v[36:37]
	v_pk_mul_f32 v[30:31], v[40:41], v[30:31]
	v_fma_f32 v34, -v44, v45, 1.0
	v_fmac_f32_e32 v45, v34, v45
	v_div_scale_f32 v34, vcc, v5, s4, v5
; __device__ __forceinline__ void filter_item(const Params& p, int l, int Lf, int t0, float* dst, float* hidT  , int wid0) {
;     ...
;     const float dmin = -3.0701134573253945f, dmax = -15.350567286626973f;
;     const float delta = fabsf(dmin + (float)tid * ((dmax - dmin) / 511.f));
; #pragma unroll
;     for (int g = 0; g < 8; ++g) { f32x4 o0, o1;
; #pragma unroll
;         for (int i = 0; i < 4; ++i) { const float tn = (float)(t0 + 4 * g + i) / (float)(Lf - 1); const float wdw = __expf(-tn * delta); o0[i] = acc0[4 * g + i] * wdw; o1[i] = acc1[4 * g + i] * wdw; }
;         *(f32x4*)(dst + (size_t)tid * Lf + t0 + 4 * g) = o0; *(f32x4*)(dst + (size_t)(512 + tid) * Lf + t0 + 4 * g) = o1; }
;     __syncthreads();
; __global__ void __launch_bounds__(512, 2) mk_fwd(Params p) {
;     ...
;             for (int it = blockIdx.x; it < 24; it += gridDim.x) filter_item(p, it >> 3, CTXL, 32 * (it & 7), (float*)(p.ws + WS_FILTC) + (size_t)(it >> 3) * 262144, (float*)(lds + 104448), wid0);
	v_mul_f32_e32 v35, v34, v45
	v_fma_f32 v40, -v44, v35, v34
	v_fmac_f32_e32 v35, v40, v45
	v_fma_f32 v34, -v44, v35, v34
	s_or_b32 s0, s27, 21
	v_div_fmas_f32 v34, v34, v45, v35
	v_cvt_f32_ubyte0_e32 v35, s0
	v_div_scale_f32 v40, s[0:1], s4, s4, v35
	v_rcp_f32_e32 v41, v40
	v_div_fixup_f32 v5, v34, s4, v5
	v_mul_f32_e64 v5, v5, |v4|
	v_mul_f32_e32 v5, 0x3fb8aa3b, v5
	v_exp_f32_e32 v34, v5
	v_fma_f32 v5, -v40, v41, 1.0
	v_fmac_f32_e32 v41, v5, v41
	v_div_scale_f32 v5, vcc, v35, s4, v35
	v_pk_mul_f32 v[32:33], v[42:43], v[32:33]
	v_mul_f32_e32 v42, v5, v41
	v_fma_f32 v43, -v40, v42, v5
	v_fmac_f32_e32 v42, v43, v41
	s_or_b32 s0, s27, 22
	v_fma_f32 v5, -v40, v42, v5
	v_cvt_f32_ubyte0_e32 v40, s0
	v_div_fmas_f32 v5, v5, v41, v42
	v_div_scale_f32 v41, s[0:1], s4, s4, v40
	v_rcp_f32_e32 v42, v41
	v_div_fixup_f32 v5, v5, s4, v35
	v_mul_f32_e64 v5, v5, |v4|
	v_mul_f32_e32 v5, 0x3fb8aa3b, v5
	v_exp_f32_e32 v35, v5
	v_fma_f32 v5, -v41, v42, 1.0
	v_fmac_f32_e32 v42, v5, v42
	v_div_scale_f32 v5, vcc, v40, s4, v40
	v_mul_f32_e32 v43, v5, v42
	v_fma_f32 v44, -v41, v43, v5
	v_fmac_f32_e32 v43, v44, v42
	s_or_b32 s0, s27, 23
	v_fma_f32 v5, -v41, v43, v5
	v_cvt_f32_ubyte0_e32 v41, s0
	v_div_fmas_f32 v5, v5, v42, v43
	v_div_scale_f32 v42, s[0:1], s4, s4, v41
	v_rcp_f32_e32 v43, v42
	v_div_fixup_f32 v5, v5, s4, v40
	v_mul_f32_e64 v5, v5, |v4|
	v_mul_f32_e32 v5, 0x3fb8aa3b, v5
	v_exp_f32_e32 v40, v5
	v_fma_f32 v5, -v42, v43, 1.0
	v_fmac_f32_e32 v43, v5, v43
	v_div_scale_f32 v5, vcc, v41, s4, v41
	v_mul_f32_e32 v44, v5, v43
	v_fma_f32 v45, -v42, v44, v5
	v_fmac_f32_e32 v44, v45, v43
	v_fma_f32 v5, -v42, v44, v5
	v_div_fmas_f32 v5, v5, v43, v44
	v_div_fixup_f32 v5, v5, s4, v41
	v_mul_f32_e64 v5, v5, |v4|
	v_mul_f32_e32 v5, 0x3fb8aa3b, v5
	s_or_b32 s0, s27, 24
	v_exp_f32_e32 v41, v5
	v_cvt_f32_ubyte0_e32 v5, s0
	global_store_dwordx4 v[0:1], v[36:39], off offset:64
	global_store_dwordx4 v[2:3], v[30:33], off offset:64
	v_pk_mul_f32 v[26:27], v[34:35], v[26:27]
	v_pk_mul_f32 v[28:29], v[40:41], v[28:29]
	v_pk_mul_f32 v[30:31], v[34:35], v[24:25]
	v_div_scale_f32 v24, s[0:1], s4, s4, v5
	v_rcp_f32_e32 v25, v24
	v_pk_mul_f32 v[32:33], v[40:41], v[22:23]
	global_store_dwordx4 v[0:1], v[26:29], off offset:80
	global_store_dwordx4 v[2:3], v[30:33], off offset:80
	s_or_b32 s0, s27, 25
	v_fma_f32 v22, -v24, v25, 1.0
	v_fmac_f32_e32 v25, v22, v25
	v_div_scale_f32 v22, vcc, v5, s4, v5
	v_mul_f32_e32 v23, v22, v25
	v_fma_f32 v26, -v24, v23, v22
	v_fmac_f32_e32 v23, v26, v25
	v_fma_f32 v22, -v24, v23, v22
	v_div_fmas_f32 v22, v22, v25, v23
	v_div_fixup_f32 v5, v22, s4, v5
	v_cvt_f32_ubyte0_e32 v22, s0
	v_div_scale_f32 v23, s[0:1], s4, s4, v22
	v_rcp_f32_e32 v25, v23
	v_mul_f32_e64 v5, v5, |v4|
	v_mul_f32_e32 v5, 0x3fb8aa3b, v5
	v_exp_f32_e32 v24, v5
	v_fma_f32 v5, -v23, v25, 1.0
	v_fmac_f32_e32 v25, v5, v25
	v_div_scale_f32 v5, vcc, v22, s4, v22
	v_mul_f32_e32 v26, v5, v25
	v_fma_f32 v27, -v23, v26, v5
	v_fmac_f32_e32 v26, v27, v25
	v_fma_f32 v5, -v23, v26, v5
	v_div_fmas_f32 v5, v5, v25, v26
	s_or_b32 s0, s27, 26
	v_div_fixup_f32 v5, v5, s4, v22
	v_cvt_f32_ubyte0_e32 v22, s0
	v_div_scale_f32 v23, s[0:1], s4, s4, v22
	v_rcp_f32_e32 v26, v23
	v_mul_f32_e64 v5, v5, |v4|
	v_mul_f32_e32 v5, 0x3fb8aa3b, v5
	v_exp_f32_e32 v25, v5
	v_fma_f32 v5, -v23, v26, 1.0
	v_fmac_f32_e32 v26, v5, v26
	v_div_scale_f32 v5, vcc, v22, s4, v22
	v_mul_f32_e32 v27, v5, v26
	v_fma_f32 v28, -v23, v27, v5
	v_fmac_f32_e32 v27, v28, v26
	v_fma_f32 v5, -v23, v27, v5
	v_div_fmas_f32 v5, v5, v26, v27
	s_or_b32 s0, s27, 27
	v_div_fixup_f32 v5, v5, s4, v22
	v_cvt_f32_ubyte0_e32 v22, s0
	v_div_scale_f32 v23, s[0:1], s4, s4, v22
	v_rcp_f32_e32 v27, v23
	v_mul_f32_e64 v5, v5, |v4|
	v_mul_f32_e32 v5, 0x3fb8aa3b, v5
	v_exp_f32_e32 v26, v5
	v_fma_f32 v5, -v23, v27, 1.0
	v_fmac_f32_e32 v27, v5, v27
	v_div_scale_f32 v5, vcc, v22, s4, v22
	v_mul_f32_e32 v28, v5, v27
	v_fma_f32 v29, -v23, v28, v5
	v_fmac_f32_e32 v28, v29, v27
	v_fma_f32 v5, -v23, v28, v5
	v_div_fmas_f32 v5, v5, v27, v28
	v_div_fixup_f32 v5, v5, s4, v22
	v_mul_f32_e64 v5, v5, |v4|
	v_mul_f32_e32 v5, 0x3fb8aa3b, v5
	s_or_b32 s0, s27, 28
	v_exp_f32_e32 v27, v5
	v_cvt_f32_ubyte0_e32 v5, s0
	v_div_scale_f32 v28, s[0:1], s4, s4, v5
	v_rcp_f32_e32 v29, v28
	v_pk_mul_f32 v[22:23], v[26:27], v[18:19]
	v_pk_mul_f32 v[20:21], v[24:25], v[20:21]
	v_pk_mul_f32 v[14:15], v[24:25], v[14:15]
	v_fma_f32 v18, -v28, v29, 1.0
	v_fmac_f32_e32 v29, v18, v29
	v_div_scale_f32 v18, vcc, v5, s4, v5
	v_mul_f32_e32 v19, v18, v29
	v_fma_f32 v24, -v28, v19, v18
	v_fmac_f32_e32 v19, v24, v29
	v_fma_f32 v18, -v28, v19, v18
	s_or_b32 s0, s27, 29
	v_div_fmas_f32 v18, v18, v29, v19
	v_cvt_f32_ubyte0_e32 v19, s0
	v_div_scale_f32 v24, s[0:1], s4, s4, v19
	v_rcp_f32_e32 v25, v24
	v_div_fixup_f32 v5, v18, s4, v5
	v_mul_f32_e64 v5, v5, |v4|
	v_mul_f32_e32 v5, 0x3fb8aa3b, v5
	v_exp_f32_e32 v18, v5
	v_fma_f32 v5, -v24, v25, 1.0
	v_fmac_f32_e32 v25, v5, v25
	v_div_scale_f32 v5, vcc, v19, s4, v19
	v_pk_mul_f32 v[16:17], v[26:27], v[16:17]
	v_mul_f32_e32 v26, v5, v25
	v_fma_f32 v27, -v24, v26, v5
	v_fmac_f32_e32 v26, v27, v25
	s_or_b32 s0, s27, 30
	v_fma_f32 v5, -v24, v26, v5
	v_cvt_f32_ubyte0_e32 v24, s0
	v_div_fmas_f32 v5, v5, v25, v26
	v_div_scale_f32 v25, s[0:1], s4, s4, v24
	v_rcp_f32_e32 v26, v25
	v_div_fixup_f32 v5, v5, s4, v19
	v_mul_f32_e64 v5, v5, |v4|
	v_mul_f32_e32 v5, 0x3fb8aa3b, v5
	v_exp_f32_e32 v19, v5
	v_fma_f32 v5, -v25, v26, 1.0
	v_fmac_f32_e32 v26, v5, v26
	v_div_scale_f32 v5, vcc, v24, s4, v24
	v_mul_f32_e32 v27, v5, v26
	v_fma_f32 v28, -v25, v27, v5
	v_fmac_f32_e32 v27, v28, v26
	s_or_b32 s0, s27, 31
	v_fma_f32 v5, -v25, v27, v5
	v_cvt_f32_ubyte0_e32 v25, s0
	v_div_fmas_f32 v5, v5, v26, v27
	v_div_scale_f32 v26, s[0:1], s4, s4, v25
	v_rcp_f32_e32 v27, v26
	v_div_fixup_f32 v5, v5, s4, v24
	v_mul_f32_e64 v5, v5, |v4|
	v_mul_f32_e32 v5, 0x3fb8aa3b, v5
	v_exp_f32_e32 v24, v5
	v_fma_f32 v5, -v26, v27, 1.0
	v_fmac_f32_e32 v27, v5, v27
	v_div_scale_f32 v5, vcc, v25, s4, v25
	v_mul_f32_e32 v28, v5, v27
	v_fma_f32 v29, -v26, v28, v5
	v_fmac_f32_e32 v28, v29, v27
	v_fma_f32 v5, -v26, v28, v5
	v_div_fmas_f32 v5, v5, v27, v28
	v_div_fixup_f32 v5, v5, s4, v25
	v_mul_f32_e64 v4, v5, |v4|
	v_mul_f32_e32 v4, 0x3fb8aa3b, v4
	v_exp_f32_e32 v25, v4
	s_add_i32 s26, s26, s24
	v_pk_mul_f32 v[10:11], v[18:19], v[10:11]
	s_cmp_gt_i32 s26, 23
	v_pk_mul_f32 v[12:13], v[24:25], v[12:13]
	global_store_dwordx4 v[0:1], v[20:23], off offset:96
	global_store_dwordx4 v[2:3], v[14:17], off offset:96
	v_pk_mul_f32 v[4:5], v[18:19], v[6:7]
	v_pk_mul_f32 v[6:7], v[24:25], v[8:9]
	global_store_dwordx4 v[0:1], v[10:13], off offset:112
	global_store_dwordx4 v[2:3], v[4:7], off offset:112
	s_barrier
	s_cbranch_scc0 .LBB0_750
	s_getpc_b64 s[98:99]
